# streaming loads of the P4-tail conversions (f32 weights, PLE input) marked nt so they do not displace GEMM operands in L2
# speedup vs baseline: 1.0135x; 1.0040x over previous
; __device__ __forceinline__ unsigned cvt_pk_bf16(float lo, float hi) { unsigned r; asm volatile("v_cvt_pk_bf16_f32 %0, %1, %2" : "=v"(r) : "v"(lo), "v"(hi)); return r; }
; __device__ __forceinline__ void p0_prologue(const Params& p, unsigned char* lds) {
;     ...
;     { bf16_t* PB = (bf16_t*)(ws + WS_PB); constexpr size_t NPB = (size_t)MT * DPLE / 8;
;       for (size_t i0 = gt; i0 < NPB; i0 += 4 * NT) { f32x4 a[4], b[4]; size_t e[4];
; #pragma unroll
;           for (int q = 0; q < 4; ++q) { const size_t i = i0 + q * NT < NPB ? i0 + q * NT : i0; e[q] = i * 8; const float* s = e[q] < (size_t)MP * DPLE ? p.in[I_PP] + e[q] : p.in[I_PS] + (e[q] - (size_t)MP * DPLE);
;               a[q] = __builtin_nontemporal_load((const f32x4*)s); b[q] = __builtin_nontemporal_load((const f32x4*)(s + 4)); }
; #pragma unroll
;           for (int q = 0; q < 4; ++q) { u32x4 w; w.x = cvt_pk_bf16(a[q][0], a[q][1]); w.y = cvt_pk_bf16(a[q][2], a[q][3]); w.z = cvt_pk_bf16(b[q][0], b[q][1]); w.w = cvt_pk_bf16(b[q][2], b[q][3]); *(u32x4*)(PB + e[q]) = w; } } }
.LBB0_708:
	s_cmp_lg_u32 s66, 0x100
	s_cbranch_scc1 .Ltail_done
	s_cmp_lt_u32 s2, 172
	s_cbranch_scc1 .Ltail_done
	s_sub_u32 s0, s2, 172
	v_readfirstlane_b32 s1, v176
	s_nop 3
	s_lshr_b32 s1, s1, 6
	s_lshl_b32 s3, s0, 3
	s_add_u32 s3, s3, s1
	v_lshlrev_b32_e32 v120, 5, v206
	v_lshlrev_b32_e32 v121, 4, v206
	v_readlane_b32 s4, v247, 4
	v_readlane_b32 s5, v247, 5
	v_readlane_b32 s6, v247, 6
	v_readlane_b32 s7, v247, 7
	s_add_u32 s8, s64, 0x1b35e00
	s_addc_u32 s9, s65, 0
	s_mul_i32 s10, s3, 12
	s_min_u32 s11, s3, 0x180
	s_add_u32 s10, s10, s11
	s_cmp_lt_u32 s3, 0x180
	s_cbranch_scc0 .Ltail_pb12
	s_add_u32 s39, s10, 0
	s_cmp_lt_u32 s39, 0x2000
	s_cselect_b32 s12, s4, s6
	s_cselect_b32 s13, s5, s7
	s_cselect_b32 s38, 0, 0x2000
	s_sub_u32 s38, s39, s38
	s_lshl_b32 s38, s38, 11
	s_add_u32 s12, s12, s38
	s_addc_u32 s13, s13, 0
	global_load_dwordx4 v[0:3], v120, s[12:13] nt
	global_load_dwordx4 v[4:7], v120, s[12:13] offset:16 nt
	s_add_u32 s39, s10, 1
	s_cmp_lt_u32 s39, 0x2000
	s_cselect_b32 s12, s4, s6
	s_cselect_b32 s13, s5, s7
	s_cselect_b32 s38, 0, 0x2000
	s_sub_u32 s38, s39, s38
	s_lshl_b32 s38, s38, 11
	s_add_u32 s12, s12, s38
	s_addc_u32 s13, s13, 0
	global_load_dwordx4 v[8:11], v120, s[12:13] nt
	global_load_dwordx4 v[12:15], v120, s[12:13] offset:16 nt
	s_add_u32 s39, s10, 2
	s_cmp_lt_u32 s39, 0x2000
	s_cselect_b32 s12, s4, s6
	s_cselect_b32 s13, s5, s7
	s_cselect_b32 s38, 0, 0x2000
	s_sub_u32 s38, s39, s38
	s_lshl_b32 s38, s38, 11
	s_add_u32 s12, s12, s38
	s_addc_u32 s13, s13, 0
	global_load_dwordx4 v[16:19], v120, s[12:13] nt
	global_load_dwordx4 v[20:23], v120, s[12:13] offset:16 nt
	s_add_u32 s39, s10, 3
	s_cmp_lt_u32 s39, 0x2000
	s_cselect_b32 s12, s4, s6
	s_cselect_b32 s13, s5, s7
	s_cselect_b32 s38, 0, 0x2000
	s_sub_u32 s38, s39, s38
	s_lshl_b32 s38, s38, 11
	s_add_u32 s12, s12, s38
	s_addc_u32 s13, s13, 0
	global_load_dwordx4 v[24:27], v120, s[12:13] nt
	global_load_dwordx4 v[28:31], v120, s[12:13] offset:16 nt
	s_add_u32 s39, s10, 4
	s_cmp_lt_u32 s39, 0x2000
	s_cselect_b32 s12, s4, s6
	s_cselect_b32 s13, s5, s7
	s_cselect_b32 s38, 0, 0x2000
	s_sub_u32 s38, s39, s38
	s_lshl_b32 s38, s38, 11
	s_add_u32 s12, s12, s38
	s_addc_u32 s13, s13, 0
	global_load_dwordx4 v[32:35], v120, s[12:13] nt
	global_load_dwordx4 v[36:39], v120, s[12:13] offset:16 nt
	s_add_u32 s39, s10, 5
	s_cmp_lt_u32 s39, 0x2000
	s_cselect_b32 s12, s4, s6
	s_cselect_b32 s13, s5, s7
	s_cselect_b32 s38, 0, 0x2000
	s_sub_u32 s38, s39, s38
	s_lshl_b32 s38, s38, 11
	s_add_u32 s12, s12, s38
	s_addc_u32 s13, s13, 0
	global_load_dwordx4 v[40:43], v120, s[12:13] nt
	global_load_dwordx4 v[44:47], v120, s[12:13] offset:16 nt
	s_add_u32 s39, s10, 6
	s_cmp_lt_u32 s39, 0x2000
	s_cselect_b32 s12, s4, s6
	s_cselect_b32 s13, s5, s7
	s_cselect_b32 s38, 0, 0x2000
	s_sub_u32 s38, s39, s38
	s_lshl_b32 s38, s38, 11
	s_add_u32 s12, s12, s38
	s_addc_u32 s13, s13, 0
	global_load_dwordx4 v[48:51], v120, s[12:13] nt
	global_load_dwordx4 v[52:55], v120, s[12:13] offset:16 nt
	s_add_u32 s39, s10, 7
	s_cmp_lt_u32 s39, 0x2000
	s_cselect_b32 s12, s4, s6
	s_cselect_b32 s13, s5, s7
	s_cselect_b32 s38, 0, 0x2000
	s_sub_u32 s38, s39, s38
	s_lshl_b32 s38, s38, 11
	s_add_u32 s12, s12, s38
	s_addc_u32 s13, s13, 0
	global_load_dwordx4 v[56:59], v120, s[12:13] nt
	global_load_dwordx4 v[60:63], v120, s[12:13] offset:16 nt
	s_add_u32 s39, s10, 8
	s_cmp_lt_u32 s39, 0x2000
	s_cselect_b32 s12, s4, s6
	s_cselect_b32 s13, s5, s7
	s_cselect_b32 s38, 0, 0x2000
	s_sub_u32 s38, s39, s38
	s_lshl_b32 s38, s38, 11
	s_add_u32 s12, s12, s38
	s_addc_u32 s13, s13, 0
	global_load_dwordx4 v[64:67], v120, s[12:13] nt
	global_load_dwordx4 v[68:71], v120, s[12:13] offset:16 nt
	s_add_u32 s39, s10, 9
	s_cmp_lt_u32 s39, 0x2000
	s_cselect_b32 s12, s4, s6
	s_cselect_b32 s13, s5, s7
	s_cselect_b32 s38, 0, 0x2000
	s_sub_u32 s38, s39, s38
	s_lshl_b32 s38, s38, 11
	s_add_u32 s12, s12, s38
	s_addc_u32 s13, s13, 0
	global_load_dwordx4 v[72:75], v120, s[12:13] nt
	global_load_dwordx4 v[76:79], v120, s[12:13] offset:16 nt
	s_add_u32 s39, s10, 10
	s_cmp_lt_u32 s39, 0x2000
	s_cselect_b32 s12, s4, s6
	s_cselect_b32 s13, s5, s7
	s_cselect_b32 s38, 0, 0x2000
	s_sub_u32 s38, s39, s38
	s_lshl_b32 s38, s38, 11
	s_add_u32 s12, s12, s38
	s_addc_u32 s13, s13, 0
	global_load_dwordx4 v[80:83], v120, s[12:13] nt
	global_load_dwordx4 v[84:87], v120, s[12:13] offset:16 nt
	s_add_u32 s39, s10, 11
	s_cmp_lt_u32 s39, 0x2000
	s_cselect_b32 s12, s4, s6
	s_cselect_b32 s13, s5, s7
	s_cselect_b32 s38, 0, 0x2000
	s_sub_u32 s38, s39, s38
	s_lshl_b32 s38, s38, 11
	s_add_u32 s12, s12, s38
	s_addc_u32 s13, s13, 0
	global_load_dwordx4 v[88:91], v120, s[12:13] nt
	global_load_dwordx4 v[92:95], v120, s[12:13] offset:16 nt
	s_add_u32 s39, s10, 12
	s_cmp_lt_u32 s39, 0x2000
	s_cselect_b32 s12, s4, s6
	s_cselect_b32 s13, s5, s7
	s_cselect_b32 s38, 0, 0x2000
	s_sub_u32 s38, s39, s38
	s_lshl_b32 s38, s38, 11
	s_add_u32 s12, s12, s38
	s_addc_u32 s13, s13, 0
	global_load_dwordx4 v[96:99], v120, s[12:13] nt
	global_load_dwordx4 v[100:103], v120, s[12:13] offset:16 nt
	s_waitcnt vmcnt(24)
	v_cvt_pk_bf16_f32 v0, v0, v1
	v_cvt_pk_bf16_f32 v1, v2, v3
	v_cvt_pk_bf16_f32 v2, v4, v5
	v_cvt_pk_bf16_f32 v3, v6, v7
	s_add_u32 s39, s10, 0
	s_lshl_b32 s38, s39, 10
	s_add_u32 s40, s8, s38
	s_addc_u32 s41, s9, 0
	global_store_dwordx4 v121, v[0:3], s[40:41]
	s_waitcnt vmcnt(23)
	v_cvt_pk_bf16_f32 v8, v8, v9
	v_cvt_pk_bf16_f32 v9, v10, v11
	v_cvt_pk_bf16_f32 v10, v12, v13
	v_cvt_pk_bf16_f32 v11, v14, v15
	s_add_u32 s39, s10, 1
	s_lshl_b32 s38, s39, 10
	s_add_u32 s40, s8, s38
	s_addc_u32 s41, s9, 0
	global_store_dwordx4 v121, v[8:11], s[40:41]
	s_waitcnt vmcnt(22)
; __device__ __forceinline__ unsigned cvt_pk_bf16(float lo, float hi) { unsigned r; asm volatile("v_cvt_pk_bf16_f32 %0, %1, %2" : "=v"(r) : "v"(lo), "v"(hi)); return r; }
; __device__ __forceinline__ void p0_prologue(const Params& p, unsigned char* lds) {
;     ...
;     { bf16_t* PB = (bf16_t*)(ws + WS_PB); constexpr size_t NPB = (size_t)MT * DPLE / 8;
;       for (size_t i0 = gt; i0 < NPB; i0 += 4 * NT) { f32x4 a[4], b[4]; size_t e[4];
; #pragma unroll
;           for (int q = 0; q < 4; ++q) { const size_t i = i0 + q * NT < NPB ? i0 + q * NT : i0; e[q] = i * 8; const float* s = e[q] < (size_t)MP * DPLE ? p.in[I_PP] + e[q] : p.in[I_PS] + (e[q] - (size_t)MP * DPLE);
;               a[q] = __builtin_nontemporal_load((const f32x4*)s); b[q] = __builtin_nontemporal_load((const f32x4*)(s + 4)); }
; #pragma unroll
;           for (int q = 0; q < 4; ++q) { u32x4 w; w.x = cvt_pk_bf16(a[q][0], a[q][1]); w.y = cvt_pk_bf16(a[q][2], a[q][3]); w.z = cvt_pk_bf16(b[q][0], b[q][1]); w.w = cvt_pk_bf16(b[q][2], b[q][3]); *(u32x4*)(PB + e[q]) = w; } } }
	v_cvt_pk_bf16_f32 v16, v16, v17
	v_cvt_pk_bf16_f32 v17, v18, v19
	v_cvt_pk_bf16_f32 v18, v20, v21
	v_cvt_pk_bf16_f32 v19, v22, v23
	s_add_u32 s39, s10, 2
	s_lshl_b32 s38, s39, 10
	s_add_u32 s40, s8, s38
	s_addc_u32 s41, s9, 0
	global_store_dwordx4 v121, v[16:19], s[40:41]
	s_waitcnt vmcnt(21)
	v_cvt_pk_bf16_f32 v24, v24, v25
	v_cvt_pk_bf16_f32 v25, v26, v27
	v_cvt_pk_bf16_f32 v26, v28, v29
	v_cvt_pk_bf16_f32 v27, v30, v31
	s_add_u32 s39, s10, 3
	s_lshl_b32 s38, s39, 10
	s_add_u32 s40, s8, s38
	s_addc_u32 s41, s9, 0
	global_store_dwordx4 v121, v[24:27], s[40:41]
	s_waitcnt vmcnt(20)
	v_cvt_pk_bf16_f32 v32, v32, v33
	v_cvt_pk_bf16_f32 v33, v34, v35
	v_cvt_pk_bf16_f32 v34, v36, v37
	v_cvt_pk_bf16_f32 v35, v38, v39
	s_add_u32 s39, s10, 4
	s_lshl_b32 s38, s39, 10
	s_add_u32 s40, s8, s38
	s_addc_u32 s41, s9, 0
	global_store_dwordx4 v121, v[32:35], s[40:41]
	s_waitcnt vmcnt(19)
	v_cvt_pk_bf16_f32 v40, v40, v41
	v_cvt_pk_bf16_f32 v41, v42, v43
	v_cvt_pk_bf16_f32 v42, v44, v45
	v_cvt_pk_bf16_f32 v43, v46, v47
	s_add_u32 s39, s10, 5
	s_lshl_b32 s38, s39, 10
	s_add_u32 s40, s8, s38
	s_addc_u32 s41, s9, 0
	global_store_dwordx4 v121, v[40:43], s[40:41]
	s_waitcnt vmcnt(18)
	v_cvt_pk_bf16_f32 v48, v48, v49
	v_cvt_pk_bf16_f32 v49, v50, v51
	v_cvt_pk_bf16_f32 v50, v52, v53
	v_cvt_pk_bf16_f32 v51, v54, v55
	s_add_u32 s39, s10, 6
	s_lshl_b32 s38, s39, 10
	s_add_u32 s40, s8, s38
	s_addc_u32 s41, s9, 0
	global_store_dwordx4 v121, v[48:51], s[40:41]
	s_waitcnt vmcnt(17)
	v_cvt_pk_bf16_f32 v56, v56, v57
	v_cvt_pk_bf16_f32 v57, v58, v59
	v_cvt_pk_bf16_f32 v58, v60, v61
	v_cvt_pk_bf16_f32 v59, v62, v63
	s_add_u32 s39, s10, 7
	s_lshl_b32 s38, s39, 10
	s_add_u32 s40, s8, s38
	s_addc_u32 s41, s9, 0
	global_store_dwordx4 v121, v[56:59], s[40:41]
	s_waitcnt vmcnt(16)
	v_cvt_pk_bf16_f32 v64, v64, v65
	v_cvt_pk_bf16_f32 v65, v66, v67
	v_cvt_pk_bf16_f32 v66, v68, v69
	v_cvt_pk_bf16_f32 v67, v70, v71
	s_add_u32 s39, s10, 8
	s_lshl_b32 s38, s39, 10
	s_add_u32 s40, s8, s38
	s_addc_u32 s41, s9, 0
	global_store_dwordx4 v121, v[64:67], s[40:41]
	s_waitcnt vmcnt(15)
	v_cvt_pk_bf16_f32 v72, v72, v73
	v_cvt_pk_bf16_f32 v73, v74, v75
	v_cvt_pk_bf16_f32 v74, v76, v77
	v_cvt_pk_bf16_f32 v75, v78, v79
	s_add_u32 s39, s10, 9
	s_lshl_b32 s38, s39, 10
	s_add_u32 s40, s8, s38
	s_addc_u32 s41, s9, 0
	global_store_dwordx4 v121, v[72:75], s[40:41]
	s_waitcnt vmcnt(14)
	v_cvt_pk_bf16_f32 v80, v80, v81
	v_cvt_pk_bf16_f32 v81, v82, v83
	v_cvt_pk_bf16_f32 v82, v84, v85
	v_cvt_pk_bf16_f32 v83, v86, v87
	s_add_u32 s39, s10, 10
	s_lshl_b32 s38, s39, 10
	s_add_u32 s40, s8, s38
	s_addc_u32 s41, s9, 0
	global_store_dwordx4 v121, v[80:83], s[40:41]
	s_waitcnt vmcnt(13)
	v_cvt_pk_bf16_f32 v88, v88, v89
	v_cvt_pk_bf16_f32 v89, v90, v91
	v_cvt_pk_bf16_f32 v90, v92, v93
	v_cvt_pk_bf16_f32 v91, v94, v95
	s_add_u32 s39, s10, 11
	s_lshl_b32 s38, s39, 10
	s_add_u32 s40, s8, s38
	s_addc_u32 s41, s9, 0
	global_store_dwordx4 v121, v[88:91], s[40:41]
	s_waitcnt vmcnt(12)
	v_cvt_pk_bf16_f32 v96, v96, v97
	v_cvt_pk_bf16_f32 v97, v98, v99
	v_cvt_pk_bf16_f32 v98, v100, v101
	v_cvt_pk_bf16_f32 v99, v102, v103
	s_add_u32 s39, s10, 12
	s_lshl_b32 s38, s39, 10
	s_add_u32 s40, s8, s38
	s_addc_u32 s41, s9, 0
	global_store_dwordx4 v121, v[96:99], s[40:41]
	s_branch .Ltail_pb_done
.Ltail_pb12:
	s_add_u32 s39, s10, 0
	s_cmp_lt_u32 s39, 0x2000
	s_cselect_b32 s12, s4, s6
	s_cselect_b32 s13, s5, s7
	s_cselect_b32 s38, 0, 0x2000
	s_sub_u32 s38, s39, s38
	s_lshl_b32 s38, s38, 11
	s_add_u32 s12, s12, s38
	s_addc_u32 s13, s13, 0
	global_load_dwordx4 v[0:3], v120, s[12:13] nt
	global_load_dwordx4 v[4:7], v120, s[12:13] offset:16 nt
	s_add_u32 s39, s10, 1
	s_cmp_lt_u32 s39, 0x2000
	s_cselect_b32 s12, s4, s6
	s_cselect_b32 s13, s5, s7
	s_cselect_b32 s38, 0, 0x2000
	s_sub_u32 s38, s39, s38
	s_lshl_b32 s38, s38, 11
	s_add_u32 s12, s12, s38
	s_addc_u32 s13, s13, 0
	global_load_dwordx4 v[8:11], v120, s[12:13] nt
	global_load_dwordx4 v[12:15], v120, s[12:13] offset:16 nt
	s_add_u32 s39, s10, 2
	s_cmp_lt_u32 s39, 0x2000
	s_cselect_b32 s12, s4, s6
	s_cselect_b32 s13, s5, s7
	s_cselect_b32 s38, 0, 0x2000
	s_sub_u32 s38, s39, s38
	s_lshl_b32 s38, s38, 11
	s_add_u32 s12, s12, s38
	s_addc_u32 s13, s13, 0
	global_load_dwordx4 v[16:19], v120, s[12:13] nt
	global_load_dwordx4 v[20:23], v120, s[12:13] offset:16 nt
	s_add_u32 s39, s10, 3
	s_cmp_lt_u32 s39, 0x2000
	s_cselect_b32 s12, s4, s6
	s_cselect_b32 s13, s5, s7
	s_cselect_b32 s38, 0, 0x2000
	s_sub_u32 s38, s39, s38
	s_lshl_b32 s38, s38, 11
	s_add_u32 s12, s12, s38
	s_addc_u32 s13, s13, 0
	global_load_dwordx4 v[24:27], v120, s[12:13] nt
	global_load_dwordx4 v[28:31], v120, s[12:13] offset:16 nt
	s_add_u32 s39, s10, 4
	s_cmp_lt_u32 s39, 0x2000
	s_cselect_b32 s12, s4, s6
	s_cselect_b32 s13, s5, s7
	s_cselect_b32 s38, 0, 0x2000
	s_sub_u32 s38, s39, s38
	s_lshl_b32 s38, s38, 11
	s_add_u32 s12, s12, s38
	s_addc_u32 s13, s13, 0
	global_load_dwordx4 v[32:35], v120, s[12:13] nt
	global_load_dwordx4 v[36:39], v120, s[12:13] offset:16 nt
	s_add_u32 s39, s10, 5
	s_cmp_lt_u32 s39, 0x2000
	s_cselect_b32 s12, s4, s6
	s_cselect_b32 s13, s5, s7
	s_cselect_b32 s38, 0, 0x2000
	s_sub_u32 s38, s39, s38
	s_lshl_b32 s38, s38, 11
	s_add_u32 s12, s12, s38
	s_addc_u32 s13, s13, 0
	global_load_dwordx4 v[40:43], v120, s[12:13] nt
	global_load_dwordx4 v[44:47], v120, s[12:13] offset:16 nt
	s_add_u32 s39, s10, 6
	s_cmp_lt_u32 s39, 0x2000
	s_cselect_b32 s12, s4, s6
	s_cselect_b32 s13, s5, s7
	s_cselect_b32 s38, 0, 0x2000
; __device__ __forceinline__ unsigned cvt_pk_bf16(float lo, float hi) { unsigned r; asm volatile("v_cvt_pk_bf16_f32 %0, %1, %2" : "=v"(r) : "v"(lo), "v"(hi)); return r; }
; __device__ __forceinline__ void p0_prologue(const Params& p, unsigned char* lds) {
;     ...
;     { bf16_t* PB = (bf16_t*)(ws + WS_PB); constexpr size_t NPB = (size_t)MT * DPLE / 8;
;       for (size_t i0 = gt; i0 < NPB; i0 += 4 * NT) { f32x4 a[4], b[4]; size_t e[4];
; #pragma unroll
;           for (int q = 0; q < 4; ++q) { const size_t i = i0 + q * NT < NPB ? i0 + q * NT : i0; e[q] = i * 8; const float* s = e[q] < (size_t)MP * DPLE ? p.in[I_PP] + e[q] : p.in[I_PS] + (e[q] - (size_t)MP * DPLE);
;               a[q] = __builtin_nontemporal_load((const f32x4*)s); b[q] = __builtin_nontemporal_load((const f32x4*)(s + 4)); }
; #pragma unroll
;           for (int q = 0; q < 4; ++q) { u32x4 w; w.x = cvt_pk_bf16(a[q][0], a[q][1]); w.y = cvt_pk_bf16(a[q][2], a[q][3]); w.z = cvt_pk_bf16(b[q][0], b[q][1]); w.w = cvt_pk_bf16(b[q][2], b[q][3]); *(u32x4*)(PB + e[q]) = w; } } }
	s_sub_u32 s38, s39, s38
	s_lshl_b32 s38, s38, 11
	s_add_u32 s12, s12, s38
	s_addc_u32 s13, s13, 0
	global_load_dwordx4 v[48:51], v120, s[12:13] nt
	global_load_dwordx4 v[52:55], v120, s[12:13] offset:16 nt
	s_add_u32 s39, s10, 7
	s_cmp_lt_u32 s39, 0x2000
	s_cselect_b32 s12, s4, s6
	s_cselect_b32 s13, s5, s7
	s_cselect_b32 s38, 0, 0x2000
	s_sub_u32 s38, s39, s38
	s_lshl_b32 s38, s38, 11
	s_add_u32 s12, s12, s38
	s_addc_u32 s13, s13, 0
	global_load_dwordx4 v[56:59], v120, s[12:13] nt
	global_load_dwordx4 v[60:63], v120, s[12:13] offset:16 nt
	s_add_u32 s39, s10, 8
	s_cmp_lt_u32 s39, 0x2000
	s_cselect_b32 s12, s4, s6
	s_cselect_b32 s13, s5, s7
	s_cselect_b32 s38, 0, 0x2000
	s_sub_u32 s38, s39, s38
	s_lshl_b32 s38, s38, 11
	s_add_u32 s12, s12, s38
	s_addc_u32 s13, s13, 0
	global_load_dwordx4 v[64:67], v120, s[12:13] nt
	global_load_dwordx4 v[68:71], v120, s[12:13] offset:16 nt
	s_add_u32 s39, s10, 9
	s_cmp_lt_u32 s39, 0x2000
	s_cselect_b32 s12, s4, s6
	s_cselect_b32 s13, s5, s7
	s_cselect_b32 s38, 0, 0x2000
	s_sub_u32 s38, s39, s38
	s_lshl_b32 s38, s38, 11
	s_add_u32 s12, s12, s38
	s_addc_u32 s13, s13, 0
	global_load_dwordx4 v[72:75], v120, s[12:13] nt
	global_load_dwordx4 v[76:79], v120, s[12:13] offset:16 nt
	s_add_u32 s39, s10, 10
	s_cmp_lt_u32 s39, 0x2000
	s_cselect_b32 s12, s4, s6
	s_cselect_b32 s13, s5, s7
	s_cselect_b32 s38, 0, 0x2000
	s_sub_u32 s38, s39, s38
	s_lshl_b32 s38, s38, 11
	s_add_u32 s12, s12, s38
	s_addc_u32 s13, s13, 0
	global_load_dwordx4 v[80:83], v120, s[12:13] nt
	global_load_dwordx4 v[84:87], v120, s[12:13] offset:16 nt
	s_add_u32 s39, s10, 11
	s_cmp_lt_u32 s39, 0x2000
	s_cselect_b32 s12, s4, s6
	s_cselect_b32 s13, s5, s7
	s_cselect_b32 s38, 0, 0x2000
	s_sub_u32 s38, s39, s38
	s_lshl_b32 s38, s38, 11
	s_add_u32 s12, s12, s38
	s_addc_u32 s13, s13, 0
	global_load_dwordx4 v[88:91], v120, s[12:13] nt
	global_load_dwordx4 v[92:95], v120, s[12:13] offset:16 nt
	s_waitcnt vmcnt(22)
	v_cvt_pk_bf16_f32 v0, v0, v1
	v_cvt_pk_bf16_f32 v1, v2, v3
	v_cvt_pk_bf16_f32 v2, v4, v5
	v_cvt_pk_bf16_f32 v3, v6, v7
	s_add_u32 s39, s10, 0
	s_lshl_b32 s38, s39, 10
	s_add_u32 s40, s8, s38
	s_addc_u32 s41, s9, 0
	global_store_dwordx4 v121, v[0:3], s[40:41]
	s_waitcnt vmcnt(21)
	v_cvt_pk_bf16_f32 v8, v8, v9
	v_cvt_pk_bf16_f32 v9, v10, v11
	v_cvt_pk_bf16_f32 v10, v12, v13
	v_cvt_pk_bf16_f32 v11, v14, v15
	s_add_u32 s39, s10, 1
	s_lshl_b32 s38, s39, 10
	s_add_u32 s40, s8, s38
	s_addc_u32 s41, s9, 0
	global_store_dwordx4 v121, v[8:11], s[40:41]
	s_waitcnt vmcnt(20)
	v_cvt_pk_bf16_f32 v16, v16, v17
	v_cvt_pk_bf16_f32 v17, v18, v19
	v_cvt_pk_bf16_f32 v18, v20, v21
	v_cvt_pk_bf16_f32 v19, v22, v23
	s_add_u32 s39, s10, 2
	s_lshl_b32 s38, s39, 10
	s_add_u32 s40, s8, s38
	s_addc_u32 s41, s9, 0
	global_store_dwordx4 v121, v[16:19], s[40:41]
	s_waitcnt vmcnt(19)
	v_cvt_pk_bf16_f32 v24, v24, v25
	v_cvt_pk_bf16_f32 v25, v26, v27
	v_cvt_pk_bf16_f32 v26, v28, v29
	v_cvt_pk_bf16_f32 v27, v30, v31
	s_add_u32 s39, s10, 3
	s_lshl_b32 s38, s39, 10
	s_add_u32 s40, s8, s38
	s_addc_u32 s41, s9, 0
	global_store_dwordx4 v121, v[24:27], s[40:41]
	s_waitcnt vmcnt(18)
	v_cvt_pk_bf16_f32 v32, v32, v33
	v_cvt_pk_bf16_f32 v33, v34, v35
	v_cvt_pk_bf16_f32 v34, v36, v37
	v_cvt_pk_bf16_f32 v35, v38, v39
	s_add_u32 s39, s10, 4
	s_lshl_b32 s38, s39, 10
	s_add_u32 s40, s8, s38
	s_addc_u32 s41, s9, 0
	global_store_dwordx4 v121, v[32:35], s[40:41]
	s_waitcnt vmcnt(17)
	v_cvt_pk_bf16_f32 v40, v40, v41
	v_cvt_pk_bf16_f32 v41, v42, v43
	v_cvt_pk_bf16_f32 v42, v44, v45
	v_cvt_pk_bf16_f32 v43, v46, v47
	s_add_u32 s39, s10, 5
	s_lshl_b32 s38, s39, 10
	s_add_u32 s40, s8, s38
	s_addc_u32 s41, s9, 0
	global_store_dwordx4 v121, v[40:43], s[40:41]
	s_waitcnt vmcnt(16)
	v_cvt_pk_bf16_f32 v48, v48, v49
	v_cvt_pk_bf16_f32 v49, v50, v51
	v_cvt_pk_bf16_f32 v50, v52, v53
	v_cvt_pk_bf16_f32 v51, v54, v55
	s_add_u32 s39, s10, 6
	s_lshl_b32 s38, s39, 10
	s_add_u32 s40, s8, s38
	s_addc_u32 s41, s9, 0
	global_store_dwordx4 v121, v[48:51], s[40:41]
	s_waitcnt vmcnt(15)
	v_cvt_pk_bf16_f32 v56, v56, v57
	v_cvt_pk_bf16_f32 v57, v58, v59
	v_cvt_pk_bf16_f32 v58, v60, v61
	v_cvt_pk_bf16_f32 v59, v62, v63
	s_add_u32 s39, s10, 7
	s_lshl_b32 s38, s39, 10
	s_add_u32 s40, s8, s38
	s_addc_u32 s41, s9, 0
	global_store_dwordx4 v121, v[56:59], s[40:41]
	s_waitcnt vmcnt(14)
	v_cvt_pk_bf16_f32 v64, v64, v65
	v_cvt_pk_bf16_f32 v65, v66, v67
	v_cvt_pk_bf16_f32 v66, v68, v69
	v_cvt_pk_bf16_f32 v67, v70, v71
	s_add_u32 s39, s10, 8
	s_lshl_b32 s38, s39, 10
	s_add_u32 s40, s8, s38
	s_addc_u32 s41, s9, 0
	global_store_dwordx4 v121, v[64:67], s[40:41]
	s_waitcnt vmcnt(13)
	v_cvt_pk_bf16_f32 v72, v72, v73
	v_cvt_pk_bf16_f32 v73, v74, v75
	v_cvt_pk_bf16_f32 v74, v76, v77
	v_cvt_pk_bf16_f32 v75, v78, v79
	s_add_u32 s39, s10, 9
	s_lshl_b32 s38, s39, 10
	s_add_u32 s40, s8, s38
	s_addc_u32 s41, s9, 0
	global_store_dwordx4 v121, v[72:75], s[40:41]
	s_waitcnt vmcnt(12)
	v_cvt_pk_bf16_f32 v80, v80, v81
	v_cvt_pk_bf16_f32 v81, v82, v83
	v_cvt_pk_bf16_f32 v82, v84, v85
	v_cvt_pk_bf16_f32 v83, v86, v87
	s_add_u32 s39, s10, 10
	s_lshl_b32 s38, s39, 10
	s_add_u32 s40, s8, s38
	s_addc_u32 s41, s9, 0
	global_store_dwordx4 v121, v[80:83], s[40:41]
	s_waitcnt vmcnt(11)
	v_cvt_pk_bf16_f32 v88, v88, v89
	v_cvt_pk_bf16_f32 v89, v90, v91
	v_cvt_pk_bf16_f32 v90, v92, v93
	v_cvt_pk_bf16_f32 v91, v94, v95
	s_add_u32 s39, s10, 11
	s_lshl_b32 s38, s39, 10
	s_add_u32 s40, s8, s38
	s_addc_u32 s41, s9, 0
	global_store_dwordx4 v121, v[88:91], s[40:41]

; __device__ __forceinline__ void tr_load(const TrItem& t, int lane, f32x4 (&v)[8], f32x4 (&g)[2]) {
;     const int r = lane & 7, k0 = 64 * t.kb + 8 * (lane >> 3); const float* src = t.W + (size_t)k0 * t.ldw + t.sc0 + 4 * r;
; #pragma unroll
;     for (int i = 0; i < 8; ++i) v[i] = __builtin_nontemporal_load((const f32x4*)(src + (size_t)i * t.ldw));
;     if (t.gain) { g[0] = *(const f32x4*)(t.gain + k0); g[1] = *(const f32x4*)(t.gain + k0 + 4); } else { g[0] = (f32x4){1.f, 1.f, 1.f, 1.f}; g[1] = g[0]; }
.Ltwgo_0:
	s_lshr_b32 s36, s38, 5
	s_and_b32 s37, s38, 31
	s_lshl_b32 s40, s36, 18
	s_lshl_b32 s41, s37, 7
	s_add_u32 s40, s40, s41
	s_add_u32 s12, s12, s40
	s_addc_u32 s13, s13, 0
	global_load_dwordx4 v[0:3], v124, s[12:13] nt
	global_load_dwordx4 v[4:7], v125, s[12:13] nt
	global_load_dwordx4 v[8:11], v126, s[12:13] nt
	global_load_dwordx4 v[12:15], v127, s[12:13] nt
	global_load_dwordx4 v[16:19], v128, s[12:13] nt
	global_load_dwordx4 v[20:23], v129, s[12:13] nt
	global_load_dwordx4 v[24:27], v130, s[12:13] nt
	global_load_dwordx4 v[28:31], v131, s[12:13] nt
	s_and_b32 s40, s36, 15
	s_lshl_b32 s40, s40, 8
	v_add_u32_e32 v40, s40, v132
	global_load_dwordx4 v[32:35], v40, s[6:7] nt
	global_load_dwordx4 v[36:39], v40, s[6:7] offset:16 nt
	s_add_u32 s39, s3, 672
	s_cmp_lt_u32 s39, 0x580
	s_cbranch_scc0 .Ltw5_1
	s_mov_b32 s38, s39
	s_mov_b32 s42, s4
	s_mov_b32 s43, s5
	s_add_u32 s46, s64, 0x1300000
	s_addc_u32 s47, s65, 0
	s_movk_i32 s48, 0xb00
	s_mov_b32 s49, 0
	s_branch .Ltwgo_1

; __device__ __forceinline__ void tr_load(const TrItem& t, int lane, f32x4 (&v)[8], f32x4 (&g)[2]) {
;     const int r = lane & 7, k0 = 64 * t.kb + 8 * (lane >> 3); const float* src = t.W + (size_t)k0 * t.ldw + t.sc0 + 4 * r;
; #pragma unroll
;     for (int i = 0; i < 8; ++i) v[i] = __builtin_nontemporal_load((const f32x4*)(src + (size_t)i * t.ldw));
;     if (t.gain) { g[0] = *(const f32x4*)(t.gain + k0); g[1] = *(const f32x4*)(t.gain + k0 + 4); } else { g[0] = (f32x4){1.f, 1.f, 1.f, 1.f}; g[1] = g[0]; }
.Ltwgo_1:
	s_lshr_b32 s50, s38, 5
	s_and_b32 s51, s38, 31
	s_lshl_b32 s40, s50, 18
	s_lshl_b32 s41, s51, 7
	s_add_u32 s40, s40, s41
	s_add_u32 s42, s42, s40
	s_addc_u32 s43, s43, 0
	global_load_dwordx4 v[48:51], v124, s[42:43] nt
	global_load_dwordx4 v[52:55], v125, s[42:43] nt
	global_load_dwordx4 v[56:59], v126, s[42:43] nt
	global_load_dwordx4 v[60:63], v127, s[42:43] nt
	global_load_dwordx4 v[64:67], v128, s[42:43] nt
	global_load_dwordx4 v[68:71], v129, s[42:43] nt
	global_load_dwordx4 v[72:75], v130, s[42:43] nt
	global_load_dwordx4 v[76:79], v131, s[42:43] nt
	s_and_b32 s40, s50, 15
	s_lshl_b32 s40, s40, 8
	v_add_u32_e32 v88, s40, v132
	global_load_dwordx4 v[80:83], v88, s[6:7] nt
	global_load_dwordx4 v[84:87], v88, s[6:7] offset:16 nt
	s_waitcnt vmcnt(10)
	s_cmp_eq_u32 s33, 1
	s_cbranch_scc1 .Ltwg_2
	v_mov_b32_e32 v32, 1.0
	v_mov_b32_e32 v33, 1.0
	v_mov_b32_e32 v34, 1.0
	v_mov_b32_e32 v35, 1.0
	v_mov_b32_e32 v36, 1.0
	v_mov_b32_e32 v37, 1.0
	v_mov_b32_e32 v38, 1.0
	v_mov_b32_e32 v39, 1.0

; __device__ __forceinline__ void tr_load(const TrItem& t, int lane, f32x4 (&v)[8], f32x4 (&g)[2]) {
;     const int r = lane & 7, k0 = 64 * t.kb + 8 * (lane >> 3); const float* src = t.W + (size_t)k0 * t.ldw + t.sc0 + 4 * r;
; #pragma unroll
;     for (int i = 0; i < 8; ++i) v[i] = __builtin_nontemporal_load((const f32x4*)(src + (size_t)i * t.ldw));
;     if (t.gain) { g[0] = *(const f32x4*)(t.gain + k0); g[1] = *(const f32x4*)(t.gain + k0 + 4); } else { g[0] = (f32x4){1.f, 1.f, 1.f, 1.f}; g[1] = g[0]; }
.Ltwgo_3:
	s_lshr_b32 s36, s38, 5
	s_and_b32 s37, s38, 31
	s_lshl_b32 s40, s36, 18
	s_lshl_b32 s41, s37, 7
	s_add_u32 s40, s40, s41
	s_add_u32 s12, s12, s40
	s_addc_u32 s13, s13, 0
	global_load_dwordx4 v[0:3], v124, s[12:13] nt
	global_load_dwordx4 v[4:7], v125, s[12:13] nt
	global_load_dwordx4 v[8:11], v126, s[12:13] nt
	global_load_dwordx4 v[12:15], v127, s[12:13] nt
	global_load_dwordx4 v[16:19], v128, s[12:13] nt
	global_load_dwordx4 v[20:23], v129, s[12:13] nt
	global_load_dwordx4 v[24:27], v130, s[12:13] nt
	global_load_dwordx4 v[28:31], v131, s[12:13] nt
	s_and_b32 s40, s36, 15
	s_lshl_b32 s40, s40, 8
	v_add_u32_e32 v40, s40, v132
	global_load_dwordx4 v[32:35], v40, s[6:7] nt
	global_load_dwordx4 v[36:39], v40, s[6:7] offset:16 nt
	s_waitcnt vmcnt(14)
	s_cmp_eq_u32 s49, 1
	s_cbranch_scc1 .Ltwg_4
	v_mov_b32_e32 v80, 1.0
	v_mov_b32_e32 v81, 1.0
	v_mov_b32_e32 v82, 1.0
	v_mov_b32_e32 v83, 1.0
	v_mov_b32_e32 v84, 1.0
	v_mov_b32_e32 v85, 1.0
	v_mov_b32_e32 v86, 1.0
	v_mov_b32_e32 v87, 1.0

; __device__ __forceinline__ void tr_load(const TrItem& t, int lane, f32x4 (&v)[8], f32x4 (&g)[2]) {
;     const int r = lane & 7, k0 = 64 * t.kb + 8 * (lane >> 3); const float* src = t.W + (size_t)k0 * t.ldw + t.sc0 + 4 * r;
; #pragma unroll
;     for (int i = 0; i < 8; ++i) v[i] = __builtin_nontemporal_load((const f32x4*)(src + (size_t)i * t.ldw));
;     if (t.gain) { g[0] = *(const f32x4*)(t.gain + k0); g[1] = *(const f32x4*)(t.gain + k0 + 4); } else { g[0] = (f32x4){1.f, 1.f, 1.f, 1.f}; g[1] = g[0]; }
.Ltwgo_5:
	s_lshr_b32 s50, s38, 5
	s_and_b32 s51, s38, 31
	s_lshl_b32 s40, s50, 18
	s_lshl_b32 s41, s51, 7
	s_add_u32 s40, s40, s41
	s_add_u32 s42, s42, s40
	s_addc_u32 s43, s43, 0
	global_load_dwordx4 v[48:51], v124, s[42:43] nt
	global_load_dwordx4 v[52:55], v125, s[42:43] nt
	global_load_dwordx4 v[56:59], v126, s[42:43] nt
	global_load_dwordx4 v[60:63], v127, s[42:43] nt
	global_load_dwordx4 v[64:67], v128, s[42:43] nt
	global_load_dwordx4 v[68:71], v129, s[42:43] nt
	global_load_dwordx4 v[72:75], v130, s[42:43] nt
	global_load_dwordx4 v[76:79], v131, s[42:43] nt
	s_and_b32 s40, s50, 15
	s_lshl_b32 s40, s40, 8
	v_add_u32_e32 v88, s40, v132
	global_load_dwordx4 v[80:83], v88, s[6:7] nt
	global_load_dwordx4 v[84:87], v88, s[6:7] offset:16 nt
	s_waitcnt vmcnt(14)
	s_cmp_eq_u32 s33, 1
	s_cbranch_scc1 .Ltwg_6
	v_mov_b32_e32 v32, 1.0
	v_mov_b32_e32 v33, 1.0
	v_mov_b32_e32 v34, 1.0
	v_mov_b32_e32 v35, 1.0
	v_mov_b32_e32 v36, 1.0
	v_mov_b32_e32 v37, 1.0
	v_mov_b32_e32 v38, 1.0
	v_mov_b32_e32 v39, 1.0
